# SwiGLU epilogue: row-independent part of the store address summed once per unit (1 mul + 1 add per row group instead of 1 mul + 4 adds), s_nop where removed adds were trans-op spacers
# speedup vs baseline: 1.0020x; 1.0020x over previous
; __device__ __forceinline__ unsigned cvtpk(float lo, float hi) { f32x2 v = {lo, hi}; bf16x2_t b = __builtin_convertvector(v, bf16x2_t); return __builtin_bit_cast(unsigned, b); }
; __device__ __forceinline__ float silu_f(float x) { return x * __builtin_amdgcn_rcpf(1.0f + __builtin_amdgcn_exp2f(-LOG2E * x)); }
;     __device__ __forceinline__ void operator()(const pg8::f32x4 (&acc)[2][2][4][2], const pg8::Unit& u, int wr, int wc, int fr, int fq) const {
;     ...
;         if (kind == EK_ACT) {
;             float rsv[2][4];
; #pragma unroll
;             for (int ai = 0; ai < 2; ++ai)
; #pragma unroll
;                 for (int m = 0; m < 4; ++m) rsv[ai][m] = fin[rowb + 128 * ai + 16 * m];
; #pragma unroll
;             for (int ai = 0; ai < 2; ++ai)
; #pragma unroll
;                 for (int m = 0; m < 4; ++m) {
;                     bf16_t* rp = o0 + (size_t)(rowb + 128 * ai + 16 * m) * ldc + u.pn * 128 + wc * 32 + (PERM ? 8 : 4) * fq;
;                     const float rs = __builtin_amdgcn_rsqf(rsv[ai][m] * (1.0f / DM) + EPS);
;                     u32x2 wn[2];
; #pragma unroll
;                     for (int n = 0; n < 2; ++n) {
;                         const pg8::f32x4 g = acc[ai][0][m][n] * rs, up = acc[ai][1][m][n] * rs;
;                         wn[n].x = cvtpk(silu_f(g[0]) * up[0], silu_f(g[1]) * up[1]); wn[n].y = cvtpk(silu_f(g[2]) * up[2], silu_f(g[3]) * up[3]);
;                     }
;                     if (PERM) { *(u32x4*)rp = (u32x4){wn[0].x, wn[0].y, wn[1].x, wn[1].y}; }
;                     else { *(u32x2*)rp = wn[0]; *(u32x2*)(rp + 16) = wn[1]; }
;                 }
.LBB0_1240:
	v_ashrrev_i32_e32 v229, 31, v228
	v_lshl_add_u64 v[66:67], v[228:229], 2, v[136:137]
	global_load_dword v64, v[66:67], off
	global_load_dword v149, v[66:67], off offset:64
	global_load_dword v146, v[66:67], off offset:128
	global_load_dword v144, v[66:67], off offset:192
	global_load_dword v142, v[66:67], off offset:512
	global_load_dword v140, v[66:67], off offset:576
	global_load_dword v138, v[66:67], off offset:640
	global_load_dword v136, v[66:67], off offset:704
	v_mad_i64_i32 v[66:67], s[8:9], v65, v228, 0
	s_lshl_b32 s8, s54, 7
	s_ashr_i32 s9, s8, 31
	s_lshl_b64 s[8:9], s[8:9], 1
	v_readlane_b32 s10, v253, 13
	s_lshl_b32 s80, s10, 1
	v_lshl_add_u64 v[212:213], v[68:69], 0, s[8:9]
	v_lshl_add_u64 v[212:213], v[212:213], 0, s[80:81]
	v_lshl_add_u64 v[212:213], v[212:213], 0, v[214:215]
	v_or_b32_e32 v148, 16, v228
	v_lshl_add_u64 v[66:67], v[66:67], 1, v[212:213]
	v_or_b32_e32 v147, 32, v228
	v_or_b32_e32 v145, 48, v228
	v_add_u32_e32 v143, 0x80, v228
	v_add_u32_e32 v141, 0x90, v228
	v_add_u32_e32 v139, 0xa0, v228
	v_add_u32_e32 v137, 0xb0, v228
	s_waitcnt vmcnt(7)
	v_fmamk_f32 v64, v64, 0x3a800000, v244
	v_rsq_f32_e32 v64, v64
	s_nop 0
	v_mul_f32_e32 v192, 0x3fb8aa3b, v64
	v_mul_f32_e32 v194, 0x3f317218, v64
	v_pk_mul_f32 v[132:133], v[132:133], v[192:193] op_sel_hi:[1,0]
	v_pk_mul_f32 v[70:71], v[134:135], v[192:193] op_sel_hi:[1,0]
	v_exp_f32_e64 v134, -v132
	v_exp_f32_e64 v135, -v133
	v_pk_mul_f32 v[124:125], v[124:125], v[194:195] op_sel_hi:[1,0]
	v_pk_mul_f32 v[126:127], v[126:127], v[194:195] op_sel_hi:[1,0]
	v_add_f32_e32 v134, 1.0, v134
	v_add_f32_e32 v135, 1.0, v135
	v_rcp_f32_e32 v134, v134
	v_rcp_f32_e32 v135, v135
	v_pk_mul_f32 v[122:123], v[122:123], v[194:195] op_sel_hi:[1,0]
	v_pk_mul_f32 v[120:121], v[120:121], v[194:195] op_sel_hi:[1,0]
	v_pk_mul_f32 v[132:133], v[132:133], v[134:135]
	s_nop 0
	v_pk_mul_f32 v[124:125], v[124:125], v[132:133]
	s_nop 0
	v_cvt_pk_bf16_f32 v124, v124, v125
	v_exp_f32_e64 v125, -v70
	s_nop 0
	v_add_f32_e32 v125, 1.0, v125
	v_rcp_f32_e32 v132, v125
	v_exp_f32_e64 v125, -v71
	s_nop 0
	v_add_f32_e32 v125, 1.0, v125
	v_rcp_f32_e32 v133, v125
	s_nop 0
	v_pk_mul_f32 v[70:71], v[70:71], v[132:133]
	s_nop 0
	v_pk_mul_f32 v[70:71], v[126:127], v[70:71]
	v_pk_mul_f32 v[126:127], v[128:129], v[192:193] op_sel_hi:[1,0]
	v_cvt_pk_bf16_f32 v125, v70, v71
	v_pk_mul_f32 v[70:71], v[130:131], v[192:193] op_sel_hi:[1,0]
	v_exp_f32_e64 v64, -v126
	s_nop 0
	v_add_f32_e32 v64, 1.0, v64
	v_rcp_f32_e32 v128, v64
	v_exp_f32_e64 v64, -v127
	s_nop 0
	v_add_f32_e32 v64, 1.0, v64
	v_rcp_f32_e32 v129, v64
	v_exp_f32_e64 v64, -v70
	v_pk_mul_f32 v[126:127], v[126:127], v[128:129]
	s_nop 0
	v_pk_mul_f32 v[120:121], v[120:121], v[126:127]
	v_add_f32_e32 v64, 1.0, v64
	v_cvt_pk_bf16_f32 v126, v120, v121
	v_rcp_f32_e32 v120, v64
	v_exp_f32_e64 v64, -v71
	s_nop 0
	v_add_f32_e32 v64, 1.0, v64
	v_rcp_f32_e32 v121, v64
	s_waitcnt vmcnt(6)
	v_fmamk_f32 v64, v149, 0x3a800000, v244
	v_rsq_f32_e32 v64, v64
	v_pk_mul_f32 v[70:71], v[70:71], v[120:121]
	s_nop 0
	v_pk_mul_f32 v[70:71], v[122:123], v[70:71]
	v_mul_f32_e32 v196, 0x3fb8aa3b, v64
	v_mul_f32_e32 v198, 0x3f317218, v64
	v_pk_mul_f32 v[116:117], v[116:117], v[196:197] op_sel_hi:[1,0]
	v_cvt_pk_bf16_f32 v127, v70, v71
	v_pk_mul_f32 v[70:71], v[118:119], v[196:197] op_sel_hi:[1,0]
	v_exp_f32_e64 v118, -v116
	v_exp_f32_e64 v119, -v117
	v_pk_mul_f32 v[112:113], v[112:113], v[198:199] op_sel_hi:[1,0]
	v_pk_mul_f32 v[114:115], v[114:115], v[198:199] op_sel_hi:[1,0]
	v_add_f32_e32 v118, 1.0, v118
	v_add_f32_e32 v119, 1.0, v119
	v_rcp_f32_e32 v118, v118
	v_rcp_f32_e32 v119, v119
	v_pk_mul_f32 v[108:109], v[108:109], v[196:197] op_sel_hi:[1,0]
	v_pk_mul_f32 v[106:107], v[106:107], v[198:199] op_sel_hi:[1,0]
	v_pk_mul_f32 v[104:105], v[104:105], v[198:199] op_sel_hi:[1,0]
	v_pk_mul_f32 v[116:117], v[116:117], v[118:119]
	global_store_dwordx4 v[66:67], v[124:127], off
	v_pk_mul_f32 v[112:113], v[112:113], v[116:117]
	v_mad_i64_i32 v[66:67], s[10:11], v65, v148, 0
	v_cvt_pk_bf16_f32 v112, v112, v113
	v_exp_f32_e64 v113, -v70
	s_nop 0
	s_nop 0
	s_nop 0
	v_add_f32_e32 v113, 1.0, v113
	v_rcp_f32_e32 v116, v113
	v_exp_f32_e64 v113, -v71
	v_lshl_add_u64 v[66:67], v[66:67], 1, v[212:213]
	v_add_f32_e32 v113, 1.0, v113
	v_rcp_f32_e32 v117, v113
	s_nop 0
	v_pk_mul_f32 v[70:71], v[70:71], v[116:117]
	s_nop 0
	v_pk_mul_f32 v[70:71], v[114:115], v[70:71]
	s_nop 0
	v_cvt_pk_bf16_f32 v113, v70, v71
	v_pk_mul_f32 v[70:71], v[110:111], v[196:197] op_sel_hi:[1,0]
	v_exp_f32_e64 v64, -v108
	s_nop 0
	v_add_f32_e32 v64, 1.0, v64
	v_rcp_f32_e32 v110, v64
	v_exp_f32_e64 v64, -v109
	s_nop 0
	v_add_f32_e32 v64, 1.0, v64
	v_rcp_f32_e32 v111, v64
	v_exp_f32_e64 v64, -v70
	v_pk_mul_f32 v[108:109], v[108:109], v[110:111]
	s_nop 0
	v_pk_mul_f32 v[104:105], v[104:105], v[108:109]
	v_add_f32_e32 v64, 1.0, v64
	v_cvt_pk_bf16_f32 v114, v104, v105
	v_rcp_f32_e32 v104, v64
	v_exp_f32_e64 v64, -v71
	s_nop 0
	v_add_f32_e32 v64, 1.0, v64
	v_rcp_f32_e32 v105, v64
	s_waitcnt vmcnt(6)
; __device__ __forceinline__ unsigned cvtpk(float lo, float hi) { f32x2 v = {lo, hi}; bf16x2_t b = __builtin_convertvector(v, bf16x2_t); return __builtin_bit_cast(unsigned, b); }
; __device__ __forceinline__ float silu_f(float x) { return x * __builtin_amdgcn_rcpf(1.0f + __builtin_amdgcn_exp2f(-LOG2E * x)); }
;     __device__ __forceinline__ void operator()(const pg8::f32x4 (&acc)[2][2][4][2], const pg8::Unit& u, int wr, int wc, int fr, int fq) const {
;     ...
;                 for (int m = 0; m < 4; ++m) rsv[ai][m] = fin[rowb + 128 * ai + 16 * m];
; #pragma unroll
;             for (int ai = 0; ai < 2; ++ai)
; #pragma unroll
;                 for (int m = 0; m < 4; ++m) {
;                     bf16_t* rp = o0 + (size_t)(rowb + 128 * ai + 16 * m) * ldc + u.pn * 128 + wc * 32 + (PERM ? 8 : 4) * fq;
;                     const float rs = __builtin_amdgcn_rsqf(rsv[ai][m] * (1.0f / DM) + EPS);
;                     u32x2 wn[2];
; #pragma unroll
;                     for (int n = 0; n < 2; ++n) {
;                         const pg8::f32x4 g = acc[ai][0][m][n] * rs, up = acc[ai][1][m][n] * rs;
;                         wn[n].x = cvtpk(silu_f(g[0]) * up[0], silu_f(g[1]) * up[1]); wn[n].y = cvtpk(silu_f(g[2]) * up[2], silu_f(g[3]) * up[3]);
;                     }
;                     if (PERM) { *(u32x4*)rp = (u32x4){wn[0].x, wn[0].y, wn[1].x, wn[1].y}; }
;                     else { *(u32x2*)rp = wn[0]; *(u32x2*)(rp + 16) = wn[1]; }
	v_fmamk_f32 v64, v146, 0x3a800000, v244
	v_rsq_f32_e32 v64, v64
	v_pk_mul_f32 v[70:71], v[70:71], v[104:105]
	s_nop 0
	v_pk_mul_f32 v[70:71], v[106:107], v[70:71]
	v_mul_f32_e32 v192, 0x3fb8aa3b, v64
	v_mul_f32_e32 v194, 0x3f317218, v64
	v_pk_mul_f32 v[100:101], v[100:101], v[192:193] op_sel_hi:[1,0]
	v_cvt_pk_bf16_f32 v115, v70, v71
	v_pk_mul_f32 v[70:71], v[102:103], v[192:193] op_sel_hi:[1,0]
	v_exp_f32_e64 v102, -v100
	v_exp_f32_e64 v103, -v101
	v_pk_mul_f32 v[96:97], v[96:97], v[194:195] op_sel_hi:[1,0]
	v_pk_mul_f32 v[98:99], v[98:99], v[194:195] op_sel_hi:[1,0]
	v_add_f32_e32 v102, 1.0, v102
	v_add_f32_e32 v103, 1.0, v103
	v_rcp_f32_e32 v102, v102
	v_rcp_f32_e32 v103, v103
	v_pk_mul_f32 v[92:93], v[92:93], v[192:193] op_sel_hi:[1,0]
	v_pk_mul_f32 v[90:91], v[90:91], v[194:195] op_sel_hi:[1,0]
	v_pk_mul_f32 v[88:89], v[88:89], v[194:195] op_sel_hi:[1,0]
	v_pk_mul_f32 v[100:101], v[100:101], v[102:103]
	global_store_dwordx4 v[66:67], v[112:115], off
	v_pk_mul_f32 v[96:97], v[96:97], v[100:101]
	v_mad_i64_i32 v[66:67], s[10:11], v65, v147, 0
	v_cvt_pk_bf16_f32 v96, v96, v97
	v_exp_f32_e64 v97, -v70
	s_nop 0
	s_nop 0
	s_nop 0
	v_add_f32_e32 v97, 1.0, v97
	v_rcp_f32_e32 v100, v97
	v_exp_f32_e64 v97, -v71
	v_lshl_add_u64 v[66:67], v[66:67], 1, v[212:213]
	v_add_f32_e32 v97, 1.0, v97
	v_rcp_f32_e32 v101, v97
	s_nop 0
	v_pk_mul_f32 v[70:71], v[70:71], v[100:101]
	s_nop 0
	v_pk_mul_f32 v[70:71], v[98:99], v[70:71]
	s_nop 0
	v_cvt_pk_bf16_f32 v97, v70, v71
	v_pk_mul_f32 v[70:71], v[94:95], v[192:193] op_sel_hi:[1,0]
	v_exp_f32_e64 v64, -v92
	s_nop 0
	v_add_f32_e32 v64, 1.0, v64
	v_rcp_f32_e32 v94, v64
	v_exp_f32_e64 v64, -v93
	s_nop 0
	v_add_f32_e32 v64, 1.0, v64
	v_rcp_f32_e32 v95, v64
	v_exp_f32_e64 v64, -v70
	v_pk_mul_f32 v[92:93], v[92:93], v[94:95]
	s_nop 0
	v_pk_mul_f32 v[88:89], v[88:89], v[92:93]
	v_add_f32_e32 v64, 1.0, v64
	v_cvt_pk_bf16_f32 v98, v88, v89
	v_rcp_f32_e32 v88, v64
	v_exp_f32_e64 v64, -v71
	s_nop 0
	v_add_f32_e32 v64, 1.0, v64
	v_rcp_f32_e32 v89, v64
	s_waitcnt vmcnt(6)
	v_fmamk_f32 v64, v144, 0x3a800000, v244
	v_rsq_f32_e32 v64, v64
	v_pk_mul_f32 v[70:71], v[70:71], v[88:89]
	s_nop 0
	v_pk_mul_f32 v[70:71], v[90:91], v[70:71]
	v_mul_f32_e32 v196, 0x3fb8aa3b, v64
	v_mul_f32_e32 v198, 0x3f317218, v64
	v_pk_mul_f32 v[80:81], v[80:81], v[198:199] op_sel_hi:[1,0]
	v_cvt_pk_bf16_f32 v99, v70, v71
	v_pk_mul_f32 v[70:71], v[84:85], v[196:197] op_sel_hi:[1,0]
	v_pk_mul_f32 v[86:87], v[86:87], v[196:197] op_sel_hi:[1,0]
	v_exp_f32_e64 v84, -v70
	v_exp_f32_e64 v85, -v71
	v_pk_mul_f32 v[76:77], v[76:77], v[196:197] op_sel_hi:[1,0]
	v_pk_mul_f32 v[82:83], v[82:83], v[198:199] op_sel_hi:[1,0]
	v_add_f32_e32 v84, 1.0, v84
	v_add_f32_e32 v85, 1.0, v85
	v_rcp_f32_e32 v84, v84
	v_rcp_f32_e32 v85, v85
	v_pk_mul_f32 v[78:79], v[78:79], v[196:197] op_sel_hi:[1,0]
	v_pk_mul_f32 v[74:75], v[74:75], v[198:199] op_sel_hi:[1,0]
	v_pk_mul_f32 v[72:73], v[72:73], v[198:199] op_sel_hi:[1,0]
	v_pk_mul_f32 v[70:71], v[70:71], v[84:85]
	v_pk_mul_f32 v[70:71], v[80:81], v[70:71]
	v_exp_f32_e64 v64, -v76
	v_cvt_pk_bf16_f32 v70, v70, v71
	v_exp_f32_e64 v71, -v86
	v_add_f32_e32 v64, 1.0, v64
	global_store_dwordx4 v[66:67], v[96:99], off
	v_mad_i64_i32 v[66:67], s[10:11], v65, v145, 0
	v_add_f32_e32 v71, 1.0, v71
	v_rcp_f32_e32 v80, v71
	v_exp_f32_e64 v71, -v87
	s_nop 0
	s_nop 0
	s_nop 0
	v_add_f32_e32 v71, 1.0, v71
	v_rcp_f32_e32 v81, v71
	v_lshl_add_u64 v[66:67], v[66:67], 1, v[212:213]
	v_pk_mul_f32 v[80:81], v[86:87], v[80:81]
	s_nop 0
	v_pk_mul_f32 v[80:81], v[82:83], v[80:81]
	s_nop 0
	v_cvt_pk_bf16_f32 v71, v80, v81
	v_rcp_f32_e32 v80, v64
	v_exp_f32_e64 v64, -v77
	s_nop 0
	v_add_f32_e32 v64, 1.0, v64
	v_rcp_f32_e32 v81, v64
	v_exp_f32_e64 v64, -v78
	v_pk_mul_f32 v[76:77], v[76:77], v[80:81]
	s_nop 0
	v_pk_mul_f32 v[72:73], v[72:73], v[76:77]
	v_add_f32_e32 v64, 1.0, v64
	v_rcp_f32_e32 v76, v64
	v_exp_f32_e64 v64, -v79
	v_cvt_pk_bf16_f32 v72, v72, v73
	v_add_f32_e32 v64, 1.0, v64
	v_rcp_f32_e32 v77, v64
	s_waitcnt vmcnt(6)
	v_fmamk_f32 v64, v142, 0x3a800000, v244
	v_rsq_f32_e32 v64, v64
	v_pk_mul_f32 v[76:77], v[78:79], v[76:77]
	s_nop 0
	v_pk_mul_f32 v[74:75], v[74:75], v[76:77]
	v_mul_f32_e32 v192, 0x3fb8aa3b, v64
	v_mul_f32_e32 v194, 0x3f317218, v64
	v_pk_mul_f32 v[60:61], v[60:61], v[192:193] op_sel_hi:[1,0]
	v_cvt_pk_bf16_f32 v73, v74, v75
	global_store_dwordx4 v[66:67], v[70:73], off
	v_pk_mul_f32 v[56:57], v[56:57], v[194:195] op_sel_hi:[1,0]
	v_pk_mul_f32 v[62:63], v[62:63], v[192:193] op_sel_hi:[1,0]
	v_exp_f32_e64 v70, -v60
	v_exp_f32_e64 v71, -v61
	v_pk_mul_f32 v[58:59], v[58:59], v[194:195] op_sel_hi:[1,0]
	v_pk_mul_f32 v[52:53], v[52:53], v[192:193] op_sel_hi:[1,0]
	v_add_f32_e32 v70, 1.0, v70
	v_add_f32_e32 v71, 1.0, v71
	v_rcp_f32_e32 v70, v70
	v_rcp_f32_e32 v71, v71
	v_pk_mul_f32 v[48:49], v[48:49], v[194:195] op_sel_hi:[1,0]
	v_pk_mul_f32 v[54:55], v[54:55], v[192:193] op_sel_hi:[1,0]
	v_pk_mul_f32 v[50:51], v[50:51], v[194:195] op_sel_hi:[1,0]
	v_pk_mul_f32 v[60:61], v[60:61], v[70:71]
	v_mad_i64_i32 v[66:67], s[10:11], v65, v143, 0
	v_pk_mul_f32 v[56:57], v[56:57], v[60:61]
	v_cvt_pk_bf16_f32 v56, v56, v57
	v_exp_f32_e64 v57, -v62
	s_nop 0
	s_nop 0
	v_add_f32_e32 v57, 1.0, v57
	v_rcp_f32_e32 v60, v57
	v_exp_f32_e64 v57, -v63
	s_nop 0
	v_add_f32_e32 v57, 1.0, v57
	v_rcp_f32_e32 v61, v57
	s_nop 0
	v_pk_mul_f32 v[60:61], v[62:63], v[60:61]
	s_nop 0
	v_pk_mul_f32 v[58:59], v[58:59], v[60:61]
	s_nop 0
	v_cvt_pk_bf16_f32 v57, v58, v59
	v_exp_f32_e64 v58, -v52
	v_exp_f32_e64 v59, -v53
	v_add_f32_e32 v58, 1.0, v58
	v_add_f32_e32 v59, 1.0, v59
	v_rcp_f32_e32 v58, v58
	v_rcp_f32_e32 v59, v59
	s_nop 0
	v_pk_mul_f32 v[52:53], v[52:53], v[58:59]
	s_nop 0
	v_pk_mul_f32 v[48:49], v[48:49], v[52:53]
	s_nop 0
	v_cvt_pk_bf16_f32 v58, v48, v49
	v_exp_f32_e64 v48, -v54
	v_exp_f32_e64 v49, -v55
	v_add_f32_e32 v48, 1.0, v48
	v_add_f32_e32 v49, 1.0, v49
	v_rcp_f32_e32 v48, v48
	v_rcp_f32_e32 v49, v49
	s_nop 0
	v_pk_mul_f32 v[48:49], v[54:55], v[48:49]
	s_nop 0
	v_pk_mul_f32 v[48:49], v[50:51], v[48:49]
	s_waitcnt vmcnt(6)
; __device__ __forceinline__ unsigned cvtpk(float lo, float hi) { f32x2 v = {lo, hi}; bf16x2_t b = __builtin_convertvector(v, bf16x2_t); return __builtin_bit_cast(unsigned, b); }
; __device__ __forceinline__ float silu_f(float x) { return x * __builtin_amdgcn_rcpf(1.0f + __builtin_amdgcn_exp2f(-LOG2E * x)); }
;     __device__ __forceinline__ void operator()(const pg8::f32x4 (&acc)[2][2][4][2], const pg8::Unit& u, int wr, int wc, int fr, int fq) const {
;     ...
;                 for (int m = 0; m < 4; ++m) rsv[ai][m] = fin[rowb + 128 * ai + 16 * m];
; #pragma unroll
;             for (int ai = 0; ai < 2; ++ai)
; #pragma unroll
;                 for (int m = 0; m < 4; ++m) {
;                     bf16_t* rp = o0 + (size_t)(rowb + 128 * ai + 16 * m) * ldc + u.pn * 128 + wc * 32 + (PERM ? 8 : 4) * fq;
;                     const float rs = __builtin_amdgcn_rsqf(rsv[ai][m] * (1.0f / DM) + EPS);
;                     u32x2 wn[2];
; #pragma unroll
;                     for (int n = 0; n < 2; ++n) {
;                         const pg8::f32x4 g = acc[ai][0][m][n] * rs, up = acc[ai][1][m][n] * rs;
;                         wn[n].x = cvtpk(silu_f(g[0]) * up[0], silu_f(g[1]) * up[1]); wn[n].y = cvtpk(silu_f(g[2]) * up[2], silu_f(g[3]) * up[3]);
;                     }
;                     if (PERM) { *(u32x4*)rp = (u32x4){wn[0].x, wn[0].y, wn[1].x, wn[1].y}; }
;                     else { *(u32x2*)rp = wn[0]; *(u32x2*)(rp + 16) = wn[1]; }
;                 }
	v_fmamk_f32 v50, v140, 0x3a800000, v244
	v_rsq_f32_e32 v50, v50
	v_cvt_pk_bf16_f32 v59, v48, v49
	v_lshl_add_u64 v[48:49], v[66:67], 1, v[212:213]
	global_store_dwordx4 v[48:49], v[56:59], off
	v_mul_f32_e32 v196, 0x3fb8aa3b, v50
	v_mul_f32_e32 v198, 0x3f317218, v50
	v_pk_mul_f32 v[44:45], v[44:45], v[196:197] op_sel_hi:[1,0]
	v_pk_mul_f32 v[46:47], v[46:47], v[196:197] op_sel_hi:[1,0]
	v_pk_mul_f32 v[42:43], v[42:43], v[198:199] op_sel_hi:[1,0]
	v_pk_mul_f32 v[40:41], v[40:41], v[198:199] op_sel_hi:[1,0]
	v_exp_f32_e64 v51, -v44
	v_mad_i64_i32 v[48:49], s[10:11], v65, v141, 0
	v_add_f32_e32 v51, 1.0, v51
	v_rcp_f32_e32 v52, v51
	v_exp_f32_e64 v51, -v45
	s_nop 0
	s_nop 0
	v_add_f32_e32 v51, 1.0, v51
	v_rcp_f32_e32 v53, v51
	v_pk_mul_f32 v[36:37], v[36:37], v[196:197] op_sel_hi:[1,0]
	v_pk_mul_f32 v[32:33], v[32:33], v[198:199] op_sel_hi:[1,0]
	v_pk_mul_f32 v[38:39], v[38:39], v[196:197] op_sel_hi:[1,0]
	v_pk_mul_f32 v[44:45], v[44:45], v[52:53]
	v_pk_mul_f32 v[34:35], v[34:35], v[198:199] op_sel_hi:[1,0]
	v_pk_mul_f32 v[40:41], v[40:41], v[44:45]
	s_nop 0
	v_cvt_pk_bf16_f32 v40, v40, v41
	v_exp_f32_e64 v41, -v46
	s_nop 0
	v_add_f32_e32 v41, 1.0, v41
	v_rcp_f32_e32 v44, v41
	v_exp_f32_e64 v41, -v47
	s_nop 0
	v_add_f32_e32 v41, 1.0, v41
	v_rcp_f32_e32 v45, v41
	s_nop 0
	v_pk_mul_f32 v[44:45], v[46:47], v[44:45]
	s_nop 0
	v_pk_mul_f32 v[42:43], v[42:43], v[44:45]
	s_nop 0
	v_cvt_pk_bf16_f32 v41, v42, v43
	v_exp_f32_e64 v42, -v36
	v_exp_f32_e64 v43, -v37
	v_add_f32_e32 v42, 1.0, v42
	v_add_f32_e32 v43, 1.0, v43
	v_rcp_f32_e32 v42, v42
	v_rcp_f32_e32 v43, v43
	s_nop 0
	v_pk_mul_f32 v[36:37], v[36:37], v[42:43]
	s_nop 0
	v_pk_mul_f32 v[32:33], v[32:33], v[36:37]
	s_nop 0
	v_cvt_pk_bf16_f32 v42, v32, v33
	v_exp_f32_e64 v32, -v38
	v_exp_f32_e64 v33, -v39
	v_add_f32_e32 v32, 1.0, v32
	v_add_f32_e32 v33, 1.0, v33
	v_rcp_f32_e32 v32, v32
	v_rcp_f32_e32 v33, v33
	s_nop 0
	v_pk_mul_f32 v[32:33], v[38:39], v[32:33]
	s_nop 0
	v_pk_mul_f32 v[32:33], v[34:35], v[32:33]
	s_waitcnt vmcnt(6)
	v_fmamk_f32 v34, v138, 0x3a800000, v244
	v_rsq_f32_e32 v34, v34
	v_cvt_pk_bf16_f32 v43, v32, v33
	v_lshl_add_u64 v[32:33], v[48:49], 1, v[212:213]
	global_store_dwordx4 v[32:33], v[40:43], off
	v_mul_f32_e32 v192, 0x3fb8aa3b, v34
	v_mul_f32_e32 v194, 0x3f317218, v34
	v_pk_mul_f32 v[28:29], v[28:29], v[192:193] op_sel_hi:[1,0]
	v_pk_mul_f32 v[30:31], v[30:31], v[192:193] op_sel_hi:[1,0]
	v_pk_mul_f32 v[26:27], v[26:27], v[194:195] op_sel_hi:[1,0]
	v_pk_mul_f32 v[24:25], v[24:25], v[194:195] op_sel_hi:[1,0]
	v_exp_f32_e64 v35, -v28
	v_mad_i64_i32 v[32:33], s[10:11], v65, v139, 0
	v_add_f32_e32 v35, 1.0, v35
	v_rcp_f32_e32 v36, v35
	v_exp_f32_e64 v35, -v29
	s_nop 0
	s_nop 0
	v_add_f32_e32 v35, 1.0, v35
	v_rcp_f32_e32 v37, v35
	v_pk_mul_f32 v[20:21], v[20:21], v[192:193] op_sel_hi:[1,0]
	v_pk_mul_f32 v[16:17], v[16:17], v[194:195] op_sel_hi:[1,0]
	v_pk_mul_f32 v[22:23], v[22:23], v[192:193] op_sel_hi:[1,0]
	v_pk_mul_f32 v[28:29], v[28:29], v[36:37]
	v_pk_mul_f32 v[18:19], v[18:19], v[194:195] op_sel_hi:[1,0]
	v_pk_mul_f32 v[24:25], v[24:25], v[28:29]
	s_nop 0
	v_cvt_pk_bf16_f32 v24, v24, v25
	v_exp_f32_e64 v25, -v30
	s_nop 0
	v_add_f32_e32 v25, 1.0, v25
	v_rcp_f32_e32 v28, v25
	v_exp_f32_e64 v25, -v31
	s_nop 0
	v_add_f32_e32 v25, 1.0, v25
	v_rcp_f32_e32 v29, v25
	s_nop 0
	v_pk_mul_f32 v[28:29], v[30:31], v[28:29]
	s_nop 0
	v_pk_mul_f32 v[26:27], v[26:27], v[28:29]
	s_nop 0
	v_cvt_pk_bf16_f32 v25, v26, v27
	v_exp_f32_e64 v26, -v20
	v_exp_f32_e64 v27, -v21
	v_add_f32_e32 v26, 1.0, v26
	v_add_f32_e32 v27, 1.0, v27
	v_rcp_f32_e32 v26, v26
	v_rcp_f32_e32 v27, v27
	s_nop 0
	v_pk_mul_f32 v[20:21], v[20:21], v[26:27]
	s_nop 0
	v_pk_mul_f32 v[16:17], v[16:17], v[20:21]
	s_nop 0
	v_cvt_pk_bf16_f32 v26, v16, v17
	v_exp_f32_e64 v16, -v22
	v_exp_f32_e64 v17, -v23
	v_add_f32_e32 v16, 1.0, v16
	v_add_f32_e32 v17, 1.0, v17
	v_rcp_f32_e32 v16, v16
	v_rcp_f32_e32 v17, v17
	s_nop 0
	v_pk_mul_f32 v[16:17], v[22:23], v[16:17]
	s_nop 0
	v_pk_mul_f32 v[16:17], v[18:19], v[16:17]
	s_waitcnt vmcnt(6)
	v_fmamk_f32 v18, v136, 0x3a800000, v244
	v_rsq_f32_e32 v18, v18
	v_cvt_pk_bf16_f32 v27, v16, v17
	v_lshl_add_u64 v[16:17], v[32:33], 1, v[212:213]
	global_store_dwordx4 v[16:17], v[24:27], off
	v_mul_f32_e32 v196, 0x3fb8aa3b, v18
	v_mul_f32_e32 v198, 0x3f317218, v18
	v_pk_mul_f32 v[12:13], v[12:13], v[196:197] op_sel_hi:[1,0]
	v_pk_mul_f32 v[14:15], v[14:15], v[196:197] op_sel_hi:[1,0]
	v_pk_mul_f32 v[10:11], v[10:11], v[198:199] op_sel_hi:[1,0]
	v_pk_mul_f32 v[8:9], v[8:9], v[198:199] op_sel_hi:[1,0]
	v_exp_f32_e64 v19, -v12
	v_mad_i64_i32 v[16:17], s[10:11], v65, v137, 0
	v_add_f32_e32 v19, 1.0, v19
	v_rcp_f32_e32 v20, v19
	v_exp_f32_e64 v19, -v13
	s_nop 0
	s_nop 0
	v_add_f32_e32 v19, 1.0, v19
	v_rcp_f32_e32 v21, v19
	v_pk_mul_f32 v[4:5], v[4:5], v[196:197] op_sel_hi:[1,0]
	v_pk_mul_f32 v[0:1], v[0:1], v[198:199] op_sel_hi:[1,0]
	v_pk_mul_f32 v[6:7], v[6:7], v[196:197] op_sel_hi:[1,0]
	v_pk_mul_f32 v[12:13], v[12:13], v[20:21]
	v_pk_mul_f32 v[2:3], v[2:3], v[198:199] op_sel_hi:[1,0]
	v_pk_mul_f32 v[8:9], v[8:9], v[12:13]
	s_nop 0
	v_cvt_pk_bf16_f32 v8, v8, v9
	v_exp_f32_e64 v9, -v14
	s_nop 0
	v_add_f32_e32 v9, 1.0, v9
	v_rcp_f32_e32 v12, v9
	v_exp_f32_e64 v9, -v15
	s_nop 0
	v_add_f32_e32 v9, 1.0, v9
	v_rcp_f32_e32 v13, v9
	s_nop 0
	v_pk_mul_f32 v[12:13], v[14:15], v[12:13]
	s_nop 0
	v_pk_mul_f32 v[10:11], v[10:11], v[12:13]
	s_nop 0
	v_cvt_pk_bf16_f32 v9, v10, v11
	v_exp_f32_e64 v10, -v4
	v_exp_f32_e64 v11, -v5
	v_add_f32_e32 v10, 1.0, v10
	v_add_f32_e32 v11, 1.0, v11
	v_rcp_f32_e32 v10, v10
	v_rcp_f32_e32 v11, v11
	s_nop 0
	v_pk_mul_f32 v[4:5], v[4:5], v[10:11]
	s_nop 0
	v_pk_mul_f32 v[0:1], v[0:1], v[4:5]
	s_nop 0
	v_cvt_pk_bf16_f32 v10, v0, v1
	v_exp_f32_e64 v0, -v6
	v_exp_f32_e64 v1, -v7
	v_add_f32_e32 v0, 1.0, v0
	v_add_f32_e32 v1, 1.0, v1
	v_rcp_f32_e32 v0, v0
	v_rcp_f32_e32 v1, v1
	s_nop 0
	v_pk_mul_f32 v[0:1], v[6:7], v[0:1]
	s_nop 0
	v_pk_mul_f32 v[0:1], v[2:3], v[0:1]
	s_nop 0
	v_cvt_pk_bf16_f32 v11, v0, v1
	v_lshl_add_u64 v[0:1], v[16:17], 1, v[212:213]
	global_store_dwordx4 v[0:1], v[8:11], off
	s_andn2_b64 vcc, exec, s[6:7]
	s_mov_b64 s[6:7], -1
	s_cbranch_vccnz .LBB0_1136
	s_branch .LBB0_1238
